# attention loop: workgroup barrier moved into the P.V block (after MFMA 7), next-tile global loads issued after MFMA 0
# speedup vs baseline: 1.0357x; 1.0009x over previous
; DI unsigned pkh2(float lo, float hi) { return __builtin_bit_cast(unsigned, __builtin_amdgcn_cvt_pkrtz(lo, hi)); }
; DI void lnmod_phase(const Args& A, LAS unsigned char* lds, int tid, int bid, int G, bool init, int l_norm, int i_norm, int l_mod, int i_mod, bool want_dt, int nrows, bool ctx_partial, const float* gprev, const float* bprev) {
;     ...
;         if (ctx_partial && row >= M_LAT) {
;             { const f32x2 st = STAT[row];
; #pragma unroll
;               for (int j = 0; j < 4; ++j) v[j] = (v[j] - st.x) * st.y * *(const f32x4*)(gprev + 256 * j + 4 * lane) + *(const f32x4*)(bprev + 256 * j + 4 * lane); }
;             const float* t0 = (const float*)(A.ws + WS_T) + (size_t)(row - M_LAT) * DM; const float* t1 = t0 + (size_t)M_CTX * DM; const float* t2 = t1 + (size_t)M_CTX * DM; const float* t3 = t2 + (size_t)M_CTX * DM;
; #pragma unroll
;             for (int j = 0; j < 4; ++j) { v[j] = v[j] * ALPHA + (*(const f32x4*)(t0 + 256 * j + 4 * lane) + *(const f32x4*)(t1 + 256 * j + 4 * lane)) + (*(const f32x4*)(t2 + 256 * j + 4 * lane) + *(const f32x4*)(t3 + 256 * j + 4 * lane)); u32x2 w_; w_.x = pkh2(v[j].x, v[j].y); w_.y = pkh2(v[j].z, v[j].w); *(u32x2*)(xout + 256 * j + 4 * lane) = w_; }
.LBB0_207:
	s_or_b64 exec, exec, s[6:7]
	v_cvt_f32_f16_sdwa v106, v92 dst_sel:DWORD dst_unused:UNUSED_PAD src0_sel:WORD_1
	v_cvt_f32_f16_e32 v90, v92
	v_cvt_f32_f16_sdwa v91, v93 dst_sel:DWORD dst_unused:UNUSED_PAD src0_sel:WORD_1
	v_cvt_f32_f16_e32 v107, v93
	v_cvt_f32_f16_sdwa v102, v94 dst_sel:DWORD dst_unused:UNUSED_PAD src0_sel:WORD_1
	v_cvt_f32_f16_e32 v92, v94
	v_cvt_f32_f16_sdwa v93, v95 dst_sel:DWORD dst_unused:UNUSED_PAD src0_sel:WORD_1
	v_cvt_f32_f16_e32 v103, v95
	v_cvt_f32_f16_sdwa v97, v98 dst_sel:DWORD dst_unused:UNUSED_PAD src0_sel:WORD_1
	v_cvt_f32_f16_e32 v96, v98
	v_cvt_f32_f16_sdwa v95, v99 dst_sel:DWORD dst_unused:UNUSED_PAD src0_sel:WORD_1
	v_cvt_f32_f16_e32 v94, v99
	v_cvt_f32_f16_sdwa v104, v88 dst_sel:DWORD dst_unused:UNUSED_PAD src0_sel:WORD_1
	v_cvt_f32_f16_e32 v100, v88
	v_cvt_f32_f16_sdwa v108, v89 dst_sel:DWORD dst_unused:UNUSED_PAD src0_sel:WORD_1
	v_cvt_f32_f16_e32 v98, v89
	v_readlane_b32 s36, v253, 23
	s_movk_i32 s6, 0x7fff
	v_readlane_b32 s38, v253, 25
	v_readlane_b32 s39, v253, 26
	v_cmp_lt_i32_e32 vcc, s6, v86
	v_readlane_b32 s37, v253, 24
	v_lshl_add_u64 v[88:89], s[38:39], 0, v[64:65]
	s_and_saveexec_b64 s[6:7], vcc
	s_cbranch_execz .LBB0_209
	v_readlane_b32 s38, v253, 25
	v_readlane_b32 s39, v253, 26
	v_add_u32_e32 v146, 0xffff8000, v86
	s_nop 1
	v_lshl_add_u64 v[110:111], s[38:39], 0, v[74:75]
	global_load_dwordx2 v[122:123], v[110:111], off
	v_readlane_b32 s36, v251, 61
	v_readlane_b32 s37, v251, 62
	s_mov_b32 s19, 0x800000
	global_load_dwordx4 v[172:175], v[68:69], off
	global_load_dwordx4 v[118:121], v[70:71], off
	global_load_dwordx4 v[176:179], v[68:69], off offset:1024
	global_load_dwordx4 v[180:183], v[70:71], off offset:1024
	global_load_dwordx4 v[184:187], v[68:69], off offset:2048
	global_load_dwordx4 v[188:191], v[70:71], off offset:2048
	global_load_dwordx4 v[192:195], v[68:69], off offset:3072
	global_load_dwordx4 v[196:199], v[70:71], off offset:3072
	s_waitcnt vmcnt(8)
	v_sub_f32_e32 v111, v106, v122
	v_sub_f32_e32 v110, v90, v122
	v_sub_f32_e32 v90, v107, v122
	v_pk_mul_f32 v[106:107], v[122:123], v[110:111] op_sel:[1,0]
	v_sub_f32_e32 v91, v91, v122
	v_pk_mul_f32 v[90:91], v[122:123], v[90:91] op_sel:[1,0]
	v_sub_f32_e32 v93, v93, v122
	v_sub_f32_e32 v97, v97, v122
	v_sub_f32_e32 v96, v96, v122
	v_sub_f32_e32 v95, v95, v122
	v_sub_f32_e32 v94, v94, v122
	v_sub_f32_e32 v101, v104, v122
	v_sub_f32_e32 v100, v100, v122
	v_sub_f32_e32 v99, v108, v122
	v_sub_f32_e32 v98, v98, v122
	v_pk_mul_f32 v[108:109], v[122:123], v[100:101] op_sel:[1,0]
	s_waitcnt vmcnt(6)
	v_pk_fma_f32 v[126:127], v[172:173], v[106:107], v[118:119]
	v_pk_fma_f32 v[90:91], v[174:175], v[90:91], v[120:121]
	v_sub_f32_e32 v107, v102, v122
	v_sub_f32_e32 v106, v92, v122
	v_sub_f32_e32 v92, v103, v122
	v_pk_mul_f32 v[102:103], v[122:123], v[92:93] op_sel:[1,0]
	v_pk_mul_f32 v[92:93], v[122:123], v[106:107] op_sel:[1,0]
	v_pk_mul_f32 v[106:107], v[122:123], v[96:97] op_sel:[1,0]
	s_waitcnt vmcnt(4)
	v_pk_fma_f32 v[92:93], v[92:93], v[176:177], v[180:181]
	v_pk_fma_f32 v[176:177], v[102:103], v[178:179], v[182:183]
	v_pk_mul_f32 v[102:103], v[122:123], v[94:95] op_sel:[1,0]
	s_waitcnt vmcnt(2)
	v_pk_fma_f32 v[184:185], v[106:107], v[184:185], v[188:189]
	v_pk_fma_f32 v[186:187], v[102:103], v[186:187], v[190:191]
	v_pk_mul_f32 v[106:107], v[122:123], v[98:99] op_sel:[1,0]
	s_waitcnt vmcnt(0)
	v_pk_fma_f32 v[192:193], v[108:109], v[192:193], v[196:197]
	v_lshlrev_b64 v[102:103], 12, v[146:147]
	v_lshl_add_u64 v[102:103], s[36:37], 0, v[102:103]
	v_lshlrev_b32_e32 v146, 2, v66
	v_lshl_add_u64 v[108:109], v[102:103], 0, v[146:147]
	v_add_co_u32_e32 v172, vcc, s19, v108
	global_load_dwordx4 v[118:121], v[108:109], off
	s_nop 1
	v_addc_co_u32_e32 v173, vcc, 0, v109, vcc
	global_load_dwordx4 v[122:125], v[172:173], off
	s_mov_b64 s[36:37], 0x800000
	v_lshl_add_u64 v[112:113], v[108:109], 0, s[36:37]
	s_mov_b64 s[36:37], 0x1000000
	v_lshl_add_u64 v[174:175], v[108:109], 0, s[36:37]
	s_mov_b64 s[36:37], 0x1800000
	v_lshl_add_u64 v[180:181], v[108:109], 0, s[36:37]
	s_mov_b32 s19, 0x1000000
	v_add_co_u32_e32 v182, vcc, s19, v108
	s_mov_b32 s19, 0x1800000
	s_nop 1
	v_addc_co_u32_e32 v183, vcc, 0, v109, vcc
	global_load_dwordx4 v[188:191], v[182:183], off
	v_add_co_u32_e32 v200, vcc, s19, v108
	s_nop 1
	v_addc_co_u32_e32 v201, vcc, 0, v109, vcc
	global_load_dwordx4 v[202:205], v[200:201], off
	global_load_dwordx4 v[218:221], v[108:109], off offset:1024
	global_load_dwordx4 v[222:225], v[112:113], off offset:1024
	global_load_dwordx4 v[226:229], v[174:175], off offset:1024
	global_load_dwordx4 v[230:233], v[180:181], off offset:1024
	s_nop 0
	v_pk_fma_f32 v[194:195], v[106:107], v[194:195], v[198:199]
	s_mov_b32 s36, 0x3fd744fd
	s_waitcnt vmcnt(6)
; DI unsigned pkh2(float lo, float hi) { return __builtin_bit_cast(unsigned, __builtin_amdgcn_cvt_pkrtz(lo, hi)); }
; DI void lnmod_phase(const Args& A, LAS unsigned char* lds, int tid, int bid, int G, bool init, int l_norm, int i_norm, int l_mod, int i_mod, bool want_dt, int nrows, bool ctx_partial, const float* gprev, const float* bprev) {
;     ...
;             const float* t0 = (const float*)(A.ws + WS_T) + (size_t)(row - M_LAT) * DM; const float* t1 = t0 + (size_t)M_CTX * DM; const float* t2 = t1 + (size_t)M_CTX * DM; const float* t3 = t2 + (size_t)M_CTX * DM;
; #pragma unroll
;             for (int j = 0; j < 4; ++j) { v[j] = v[j] * ALPHA + (*(const f32x4*)(t0 + 256 * j + 4 * lane) + *(const f32x4*)(t1 + 256 * j + 4 * lane)) + (*(const f32x4*)(t2 + 256 * j + 4 * lane) + *(const f32x4*)(t3 + 256 * j + 4 * lane)); u32x2 w_; w_.x = pkh2(v[j].x, v[j].y); w_.y = pkh2(v[j].z, v[j].w); *(u32x2*)(xout + 256 * j + 4 * lane) = w_; }
	v_pk_add_f32 v[172:173], v[120:121], v[124:125]
	s_nop 0
	v_pk_fma_f32 v[90:91], v[90:91], s[36:37], v[172:173] op_sel_hi:[1,0,1]
	s_nop 0
	v_pk_add_f32 v[114:115], v[118:119], v[122:123]
	v_pk_fma_f32 v[114:115], v[126:127], s[36:37], v[114:115] op_sel_hi:[1,0,1]
	s_nop 0
	s_mov_b32 s19, 0x21200000
	s_waitcnt vmcnt(4)
	v_pk_add_f32 v[200:201], v[190:191], v[204:205]
	v_pk_add_f32 v[188:189], v[188:189], v[202:203]
	v_pk_add_f32 v[200:201], v[90:91], v[200:201]
	v_pk_add_f32 v[90:91], v[114:115], v[188:189]
	v_add_co_u32_e32 v114, vcc, s19, v88
	v_cvt_pkrtz_f16_f32 v188, v90, v91
	v_cvt_pkrtz_f16_f32 v189, v200, v201
	v_addc_co_u32_e32 v115, vcc, 0, v89, vcc
	global_store_dwordx2 v[114:115], v[188:189], off
	s_nop 0
	s_waitcnt vmcnt(3)
	v_pk_add_f32 v[220:221], v[220:221], v[224:225]
	v_pk_add_f32 v[218:219], v[218:219], v[222:223]
	v_pk_fma_f32 v[176:177], v[176:177], s[36:37], v[220:221] op_sel_hi:[1,0,1]
	v_pk_fma_f32 v[92:93], v[92:93], s[36:37], v[218:219] op_sel_hi:[1,0,1]
	s_waitcnt vmcnt(1)
	v_pk_add_f32 v[228:229], v[228:229], v[232:233]
	v_pk_add_f32 v[226:227], v[226:227], v[230:231]
	v_pk_add_f32 v[126:127], v[176:177], v[228:229]
	v_pk_add_f32 v[92:93], v[92:93], v[226:227]
	v_cvt_pkrtz_f16_f32 v177, v126, v127
	v_cvt_pkrtz_f16_f32 v176, v92, v93
	global_store_dwordx2 v[114:115], v[176:177], off offset:512
	global_load_dwordx4 v[118:121], v[108:109], off offset:2048
	global_load_dwordx4 v[122:125], v[112:113], off offset:2048
	global_load_dwordx4 v[176:179], v[174:175], off offset:2048
	global_load_dwordx4 v[188:191], v[180:181], off offset:2048
	global_load_dwordx4 v[196:199], v[108:109], off offset:3072
	global_load_dwordx4 v[202:205], v[112:113], off offset:3072
	global_load_dwordx4 v[218:221], v[174:175], off offset:3072
	global_load_dwordx4 v[104:107], v[180:181], off offset:3072
	s_waitcnt vmcnt(6)
	v_pk_add_f32 v[110:111], v[120:121], v[124:125]
	v_pk_add_f32 v[118:119], v[118:119], v[122:123]
	v_pk_fma_f32 v[110:111], v[186:187], s[36:37], v[110:111] op_sel_hi:[1,0,1]
	v_pk_fma_f32 v[122:123], v[184:185], s[36:37], v[118:119] op_sel_hi:[1,0,1]
	s_waitcnt vmcnt(4)
	v_pk_add_f32 v[178:179], v[178:179], v[190:191]
	v_pk_add_f32 v[188:189], v[176:177], v[188:189]
	v_pk_add_f32 v[176:177], v[110:111], v[178:179]
	v_pk_add_f32 v[178:179], v[122:123], v[188:189]
	v_cvt_pkrtz_f16_f32 v111, v176, v177
	v_cvt_pkrtz_f16_f32 v110, v178, v179
	global_store_dwordx2 v[114:115], v[110:111], off offset:1024
	s_nop 0
	s_waitcnt vmcnt(3)
	v_pk_add_f32 v[198:199], v[198:199], v[204:205]
	v_pk_add_f32 v[196:197], v[196:197], v[202:203]
	v_pk_fma_f32 v[198:199], v[194:195], s[36:37], v[198:199] op_sel_hi:[1,0,1]
	v_pk_fma_f32 v[196:197], v[192:193], s[36:37], v[196:197] op_sel_hi:[1,0,1]
	s_nop 0
	s_waitcnt vmcnt(1)
	v_pk_add_f32 v[220:221], v[220:221], v[106:107]
	v_pk_add_f32 v[104:105], v[218:219], v[104:105]
	v_pk_add_f32 v[218:219], v[198:199], v[220:221]
	v_pk_add_f32 v[220:221], v[196:197], v[104:105]
	v_cvt_pkrtz_f16_f32 v105, v218, v219
	v_cvt_pkrtz_f16_f32 v104, v220, v221
	global_store_dwordx2 v[114:115], v[104:105], off offset:1536
	v_mov_b32_e32 v106, v91
	v_mov_b32_e32 v107, v200
	v_mov_b32_e32 v91, v201
	v_mov_b32_e32 v200, v93
	v_mov_b32_e32 v201, v126
	v_mov_b32_e32 v93, v127
	v_mov_b32_e32 v104, v221
	v_mov_b32_e32 v196, v219
	v_mov_b32_e32 v94, v176
	v_mov_b32_e32 v95, v177
	v_mov_b32_e32 v96, v178
	v_mov_b32_e32 v97, v179
	v_mov_b32_e32 v98, v218
	v_mov_b32_e32 v100, v220
	v_mov_b32_e32 v102, v200
	v_mov_b32_e32 v103, v201
	v_mov_b32_e32 v108, v196

; DI void lnmod_phase(const Args& A, LAS unsigned char* lds, int tid, int bid, int G, bool init, int l_norm, int i_norm, int l_mod, int i_mod, bool want_dt, int nrows, bool ctx_partial, const float* gprev, const float* bprev) {
;     ...
;         if (ctx_partial && row >= M_LAT) {
;             { const f32x2 st = STAT[row];
; #pragma unroll
;               for (int j = 0; j < 4; ++j) v[j] = (v[j] - st.x) * st.y * *(const f32x4*)(gprev + 256 * j + 4 * lane) + *(const f32x4*)(bprev + 256 * j + 4 * lane); }
.LBB0_231:
	s_or_b64 exec, exec, s[4:5]
	v_cvt_f32_f16_sdwa v108, v66 dst_sel:DWORD dst_unused:UNUSED_PAD src0_sel:WORD_1
	v_cvt_f32_f16_e32 v64, v66
	v_cvt_f32_f16_sdwa v65, v67 dst_sel:DWORD dst_unused:UNUSED_PAD src0_sel:WORD_1
	v_cvt_f32_f16_e32 v109, v67
	v_cvt_f32_f16_sdwa v66, v72 dst_sel:DWORD dst_unused:UNUSED_PAD src0_sel:WORD_1
	v_cvt_f32_f16_e32 v68, v72
	v_cvt_f32_f16_sdwa v69, v73 dst_sel:DWORD dst_unused:UNUSED_PAD src0_sel:WORD_1
	v_cvt_f32_f16_e32 v67, v73
	v_cvt_f32_f16_sdwa v73, v70 dst_sel:DWORD dst_unused:UNUSED_PAD src0_sel:WORD_1
	v_cvt_f32_f16_e32 v72, v70
	v_cvt_f32_f16_sdwa v75, v71 dst_sel:DWORD dst_unused:UNUSED_PAD src0_sel:WORD_1
	v_cvt_f32_f16_e32 v74, v71
	v_cvt_f32_f16_sdwa v70, v76 dst_sel:DWORD dst_unused:UNUSED_PAD src0_sel:WORD_1
	v_cvt_f32_f16_e32 v76, v76
	v_cvt_f32_f16_sdwa v106, v77 dst_sel:DWORD dst_unused:UNUSED_PAD src0_sel:WORD_1
	v_cvt_f32_f16_e32 v78, v77
	s_movk_i32 s4, 0x7fff
	v_cmp_lt_i32_e32 vcc, s4, v118
	v_readlane_b32 s4, v253, 37
	v_readlane_b32 s40, v253, 23
	v_readlane_b32 s5, v253, 38
	v_readlane_b32 s42, v253, 25
	v_readlane_b32 s43, v253, 26
	s_and_b64 s[36:37], s[4:5], vcc
	v_readlane_b32 s41, v253, 24
	v_lshl_add_u64 v[104:105], s[42:43], 0, v[82:83]
	s_and_saveexec_b64 s[4:5], s[36:37]
	s_cbranch_execz .LBB0_233
	v_readlane_b32 s38, v253, 25
	v_readlane_b32 s39, v253, 26
	v_add_u32_e32 v146, 0xffff8000, v118
	s_nop 1
	v_lshl_add_u64 v[110:111], s[38:39], 0, v[92:93]
	global_load_dwordx2 v[120:121], v[110:111], off
	v_readlane_b32 s36, v251, 61
	v_readlane_b32 s37, v251, 62
	s_mov_b32 s7, 0x800000
	global_load_dwordx4 v[130:133], v[86:87], off
	global_load_dwordx4 v[112:115], v[88:89], off
	global_load_dwordx4 v[134:137], v[86:87], off offset:1024
	global_load_dwordx4 v[138:141], v[88:89], off offset:1024
	global_load_dwordx4 v[154:157], v[86:87], off offset:2048
	global_load_dwordx4 v[160:163], v[88:89], off offset:2048
	global_load_dwordx4 v[164:167], v[86:87], off offset:3072
	global_load_dwordx4 v[168:171], v[88:89], off offset:3072
	s_waitcnt vmcnt(8)
	v_sub_f32_e32 v111, v108, v120
	v_sub_f32_e32 v110, v64, v120
	v_sub_f32_e32 v64, v109, v120
	v_pk_mul_f32 v[122:123], v[120:121], v[110:111] op_sel:[1,0]
	v_sub_f32_e32 v65, v65, v120
	v_pk_mul_f32 v[64:65], v[120:121], v[64:65] op_sel:[1,0]
	v_sub_f32_e32 v69, v69, v120
	s_waitcnt vmcnt(6)
	v_pk_fma_f32 v[114:115], v[132:133], v[64:65], v[114:115]
	v_sub_f32_e32 v65, v66, v120
	v_sub_f32_e32 v64, v68, v120
	v_sub_f32_e32 v68, v67, v120
	v_pk_fma_f32 v[128:129], v[130:131], v[122:123], v[112:113]
	v_pk_mul_f32 v[112:113], v[120:121], v[68:69] op_sel:[1,0]
	v_pk_mul_f32 v[68:69], v[120:121], v[64:65] op_sel:[1,0]
	s_waitcnt vmcnt(4)
	v_pk_fma_f32 v[68:69], v[68:69], v[134:135], v[138:139]
	v_pk_fma_f32 v[138:139], v[112:113], v[136:137], v[140:141]
	v_sub_f32_e32 v135, v73, v120
	v_sub_f32_e32 v134, v72, v120
	v_sub_f32_e32 v137, v75, v120
	v_sub_f32_e32 v136, v74, v120
	v_pk_mul_f32 v[140:141], v[120:121], v[136:137] op_sel:[1,0]
	v_pk_mul_f32 v[112:113], v[120:121], v[134:135] op_sel:[1,0]
	s_waitcnt vmcnt(2)
	v_pk_fma_f32 v[160:161], v[112:113], v[154:155], v[160:161]
	v_pk_fma_f32 v[162:163], v[140:141], v[156:157], v[162:163]
	v_sub_f32_e32 v154, v76, v120
	v_sub_f32_e32 v156, v78, v120
	v_sub_f32_e32 v155, v70, v120
	v_sub_f32_e32 v157, v106, v120
	v_pk_mul_f32 v[154:155], v[120:121], v[154:155] op_sel:[1,0]
	v_pk_mul_f32 v[70:71], v[120:121], v[156:157] op_sel:[1,0]
	s_waitcnt vmcnt(0)
; DI unsigned pkh2(float lo, float hi) { return __builtin_bit_cast(unsigned, __builtin_amdgcn_cvt_pkrtz(lo, hi)); }
; DI void lnmod_phase(const Args& A, LAS unsigned char* lds, int tid, int bid, int G, bool init, int l_norm, int i_norm, int l_mod, int i_mod, bool want_dt, int nrows, bool ctx_partial, const float* gprev, const float* bprev) {
;     ...
;             const float* t0 = (const float*)(A.ws + WS_T) + (size_t)(row - M_LAT) * DM; const float* t1 = t0 + (size_t)M_CTX * DM; const float* t2 = t1 + (size_t)M_CTX * DM; const float* t3 = t2 + (size_t)M_CTX * DM;
; #pragma unroll
;             for (int j = 0; j < 4; ++j) { v[j] = v[j] * ALPHA + (*(const f32x4*)(t0 + 256 * j + 4 * lane) + *(const f32x4*)(t1 + 256 * j + 4 * lane)) + (*(const f32x4*)(t2 + 256 * j + 4 * lane) + *(const f32x4*)(t3 + 256 * j + 4 * lane)); u32x2 w_; w_.x = pkh2(v[j].x, v[j].y); w_.y = pkh2(v[j].z, v[j].w); *(u32x2*)(xout + 256 * j + 4 * lane) = w_; }
	v_pk_fma_f32 v[156:157], v[154:155], v[164:165], v[168:169]
	v_lshlrev_b64 v[64:65], 12, v[146:147]
	v_lshl_add_u64 v[64:65], s[36:37], 0, v[64:65]
	v_lshlrev_b32_e32 v146, 2, v84
	v_lshl_add_u64 v[110:111], v[64:65], 0, v[146:147]
	v_add_co_u32_e32 v130, vcc, s7, v110
	global_load_dwordx4 v[120:123], v[110:111], off
	s_nop 1
	v_addc_co_u32_e32 v131, vcc, 0, v111, vcc
	global_load_dwordx4 v[124:127], v[130:131], off
	s_mov_b64 s[36:37], 0x800000
	v_lshl_add_u64 v[132:133], v[110:111], 0, s[36:37]
	s_mov_b64 s[36:37], 0x1000000
	v_lshl_add_u64 v[76:77], v[110:111], 0, s[36:37]
	s_mov_b64 s[36:37], 0x1800000
	v_lshl_add_u64 v[134:135], v[110:111], 0, s[36:37]
	s_mov_b32 s7, 0x1000000
	v_add_co_u32_e32 v136, vcc, s7, v110
	s_mov_b32 s7, 0x1800000
	s_nop 1
	v_addc_co_u32_e32 v137, vcc, 0, v111, vcc
	global_load_dwordx4 v[172:175], v[136:137], off
	v_add_co_u32_e32 v142, vcc, s7, v110
	s_nop 1
	v_addc_co_u32_e32 v143, vcc, 0, v111, vcc
	global_load_dwordx4 v[176:179], v[142:143], off
	global_load_dwordx4 v[180:183], v[110:111], off offset:1024
	global_load_dwordx4 v[184:187], v[132:133], off offset:1024
	global_load_dwordx4 v[188:191], v[76:77], off offset:1024
	global_load_dwordx4 v[192:195], v[134:135], off offset:1024
	global_load_dwordx4 v[196:199], v[110:111], off offset:2048
	global_load_dwordx4 v[200:203], v[132:133], off offset:2048
	global_load_dwordx4 v[204:207], v[76:77], off offset:2048
	global_load_dwordx4 v[218:221], v[134:135], off offset:2048
	global_load_dwordx4 v[222:225], v[110:111], off offset:3072
	global_load_dwordx4 v[226:229], v[132:133], off offset:3072
	global_load_dwordx4 v[230:233], v[76:77], off offset:3072
	global_load_dwordx4 v[234:237], v[134:135], off offset:3072
	s_nop 0
	v_pk_fma_f32 v[70:71], v[70:71], v[166:167], v[170:171]
	s_mov_b32 s36, 0x3fd744fd
	s_waitcnt vmcnt(14)
	v_pk_add_f32 v[130:131], v[122:123], v[126:127]
	v_pk_add_f32 v[106:107], v[120:121], v[124:125]
	v_pk_fma_f32 v[130:131], v[114:115], s[36:37], v[130:131] op_sel_hi:[1,0,1]
	v_pk_fma_f32 v[114:115], v[128:129], s[36:37], v[106:107] op_sel_hi:[1,0,1]
	s_nop 0
	s_mov_b32 s7, 0x21200000
	s_nop 0
	s_waitcnt vmcnt(12)
	v_pk_add_f32 v[142:143], v[174:175], v[178:179]
	v_pk_add_f32 v[172:173], v[172:173], v[176:177]
	v_pk_add_f32 v[142:143], v[130:131], v[142:143]
	v_pk_add_f32 v[130:131], v[114:115], v[172:173]
	v_add_co_u32_e32 v114, vcc, s7, v104
	v_cvt_pkrtz_f16_f32 v172, v130, v131
	v_cvt_pkrtz_f16_f32 v173, v142, v143
	v_addc_co_u32_e32 v115, vcc, 0, v105, vcc
	global_store_dwordx2 v[114:115], v[172:173], off
	s_nop 0
	s_waitcnt vmcnt(11)
	v_pk_add_f32 v[182:183], v[182:183], v[186:187]
	v_pk_add_f32 v[180:181], v[180:181], v[184:185]
	v_pk_fma_f32 v[138:139], v[138:139], s[36:37], v[182:183] op_sel_hi:[1,0,1]
	v_pk_fma_f32 v[68:69], v[68:69], s[36:37], v[180:181] op_sel_hi:[1,0,1]
	s_waitcnt vmcnt(9)
	v_pk_add_f32 v[190:191], v[190:191], v[194:195]
	v_pk_add_f32 v[188:189], v[188:189], v[192:193]
	v_pk_add_f32 v[128:129], v[138:139], v[190:191]
	v_pk_add_f32 v[68:69], v[68:69], v[188:189]
	v_cvt_pkrtz_f16_f32 v139, v128, v129
	v_cvt_pkrtz_f16_f32 v138, v68, v69
	global_store_dwordx2 v[114:115], v[138:139], off offset:512
	s_waitcnt vmcnt(8)
	v_pk_add_f32 v[138:139], v[198:199], v[202:203]
	v_pk_add_f32 v[196:197], v[196:197], v[200:201]
	v_pk_fma_f32 v[138:139], v[162:163], s[36:37], v[138:139] op_sel_hi:[1,0,1]
	v_pk_fma_f32 v[200:201], v[160:161], s[36:37], v[196:197] op_sel_hi:[1,0,1]
	s_waitcnt vmcnt(6)
	v_pk_add_f32 v[206:207], v[206:207], v[220:221]
	v_pk_add_f32 v[204:205], v[204:205], v[218:219]
	v_pk_add_f32 v[206:207], v[138:139], v[206:207]
	v_pk_add_f32 v[204:205], v[200:201], v[204:205]
	v_cvt_pkrtz_f16_f32 v139, v206, v207
	v_cvt_pkrtz_f16_f32 v138, v204, v205
	global_store_dwordx2 v[114:115], v[138:139], off offset:1024
	s_nop 0
	s_waitcnt vmcnt(5)
	v_pk_add_f32 v[224:225], v[224:225], v[228:229]
	v_pk_add_f32 v[222:223], v[222:223], v[226:227]
	v_pk_fma_f32 v[70:71], v[70:71], s[36:37], v[224:225] op_sel_hi:[1,0,1]
	v_pk_fma_f32 v[156:157], v[156:157], s[36:37], v[222:223] op_sel_hi:[1,0,1]
	s_nop 0
	s_waitcnt vmcnt(3)
	v_pk_add_f32 v[236:237], v[232:233], v[236:237]
	v_pk_add_f32 v[234:235], v[230:231], v[234:235]
	v_pk_add_f32 v[236:237], v[70:71], v[236:237]
	v_pk_add_f32 v[234:235], v[156:157], v[234:235]
	v_cvt_pkrtz_f16_f32 v157, v236, v237
	v_cvt_pkrtz_f16_f32 v156, v234, v235
	global_store_dwordx2 v[114:115], v[156:157], off offset:1536
	v_mov_b32_e32 v230, v131
	v_mov_b32_e32 v231, v142
	v_mov_b32_e32 v131, v143
	v_mov_b32_e32 v156, v69
	v_mov_b32_e32 v157, v128
	v_mov_b32_e32 v69, v129
	v_mov_b32_e32 v70, v235
	v_mov_b32_e32 v142, v237
	v_mov_b32_e32 v64, v130
	v_mov_b32_e32 v65, v131
	v_mov_b32_e32 v66, v156
	v_mov_b32_e32 v67, v157
	v_mov_b32_e32 v72, v204
	v_mov_b32_e32 v73, v205
	v_mov_b32_e32 v74, v206
	v_mov_b32_e32 v75, v207
	v_mov_b32_e32 v76, v234
	v_mov_b32_e32 v78, v236
	v_mov_b32_e32 v106, v142
	v_mov_b32_e32 v108, v230
	v_mov_b32_e32 v109, v231

; DI void lnmod_phase(const Args& A, LAS unsigned char* lds, int tid, int bid, int G, bool init, int l_norm, int i_norm, int l_mod, int i_mod, bool want_dt, int nrows, bool ctx_partial, const float* gprev, const float* bprev) {
;     ...
;         if (ctx_partial && row >= M_LAT) {
;             { const f32x2 st = STAT[row];
; #pragma unroll
;               for (int j = 0; j < 4; ++j) v[j] = (v[j] - st.x) * st.y * *(const f32x4*)(gprev + 256 * j + 4 * lane) + *(const f32x4*)(bprev + 256 * j + 4 * lane); }
.LBB0_282:
	s_or_b64 exec, exec, s[4:5]
	v_cvt_f32_f16_sdwa v104, v90 dst_sel:DWORD dst_unused:UNUSED_PAD src0_sel:WORD_1
	v_cvt_f32_f16_e32 v88, v90
	v_cvt_f32_f16_sdwa v89, v91 dst_sel:DWORD dst_unused:UNUSED_PAD src0_sel:WORD_1
	v_cvt_f32_f16_e32 v105, v91
	v_cvt_f32_f16_sdwa v100, v92 dst_sel:DWORD dst_unused:UNUSED_PAD src0_sel:WORD_1
	v_cvt_f32_f16_e32 v90, v92
	v_cvt_f32_f16_sdwa v91, v93 dst_sel:DWORD dst_unused:UNUSED_PAD src0_sel:WORD_1
	v_cvt_f32_f16_e32 v101, v93
	v_cvt_f32_f16_sdwa v95, v96 dst_sel:DWORD dst_unused:UNUSED_PAD src0_sel:WORD_1
	v_cvt_f32_f16_e32 v94, v96
	v_cvt_f32_f16_sdwa v93, v97 dst_sel:DWORD dst_unused:UNUSED_PAD src0_sel:WORD_1
	v_cvt_f32_f16_e32 v92, v97
	v_cvt_f32_f16_sdwa v102, v86 dst_sel:DWORD dst_unused:UNUSED_PAD src0_sel:WORD_1
	v_cvt_f32_f16_e32 v98, v86
	v_cvt_f32_f16_sdwa v106, v87 dst_sel:DWORD dst_unused:UNUSED_PAD src0_sel:WORD_1
	v_cvt_f32_f16_e32 v96, v87
	s_movk_i32 s4, 0x7fff
	v_cmp_lt_i32_e32 vcc, s4, v84
	v_readlane_b32 s4, v253, 37
	v_readlane_b32 s28, v253, 23
	v_readlane_b32 s5, v253, 38
	v_readlane_b32 s30, v253, 25
	v_readlane_b32 s31, v253, 26
	s_and_b64 s[24:25], s[4:5], vcc
	v_readlane_b32 s29, v253, 24
	v_lshl_add_u64 v[86:87], s[30:31], 0, v[64:65]
	s_and_saveexec_b64 s[4:5], s[24:25]
	s_cbranch_execz .LBB0_284
	v_readlane_b32 s26, v253, 25
	v_readlane_b32 s27, v253, 26
	v_add_u32_e32 v146, 0xffff8000, v84
	s_nop 1
	v_lshl_add_u64 v[108:109], s[26:27], 0, v[74:75]
	global_load_dwordx2 v[116:117], v[108:109], off
	v_readlane_b32 s24, v251, 61
	v_readlane_b32 s25, v251, 62
	s_mov_b32 s9, 0x800000
	global_load_dwordx4 v[124:127], v[68:69], off
	global_load_dwordx4 v[112:115], v[70:71], off
	global_load_dwordx4 v[128:131], v[68:69], off offset:1024
	global_load_dwordx4 v[132:135], v[70:71], off offset:1024
	global_load_dwordx4 v[136:139], v[68:69], off offset:2048
	global_load_dwordx4 v[140:143], v[70:71], off offset:2048
	global_load_dwordx4 v[154:157], v[68:69], off offset:3072
	global_load_dwordx4 v[160:163], v[70:71], off offset:3072
	s_waitcnt vmcnt(8)
	v_sub_f32_e32 v109, v104, v116
	v_sub_f32_e32 v108, v88, v116
	v_sub_f32_e32 v88, v105, v116
	v_pk_mul_f32 v[104:105], v[116:117], v[108:109] op_sel:[1,0]
	v_sub_f32_e32 v89, v89, v116
	v_pk_mul_f32 v[88:89], v[116:117], v[88:89] op_sel:[1,0]
	v_sub_f32_e32 v91, v91, v116
	v_sub_f32_e32 v95, v95, v116
	v_sub_f32_e32 v94, v94, v116
	v_sub_f32_e32 v93, v93, v116
	v_sub_f32_e32 v92, v92, v116
	v_sub_f32_e32 v99, v102, v116
	v_sub_f32_e32 v98, v98, v116
	v_sub_f32_e32 v97, v106, v116
	v_sub_f32_e32 v96, v96, v116
	v_pk_mul_f32 v[106:107], v[116:117], v[98:99] op_sel:[1,0]
	s_waitcnt vmcnt(6)
	v_pk_fma_f32 v[120:121], v[124:125], v[104:105], v[112:113]
	v_pk_fma_f32 v[88:89], v[126:127], v[88:89], v[114:115]
	v_sub_f32_e32 v105, v100, v116
	v_sub_f32_e32 v104, v90, v116
	v_sub_f32_e32 v90, v101, v116
	v_pk_mul_f32 v[100:101], v[116:117], v[90:91] op_sel:[1,0]
	v_pk_mul_f32 v[90:91], v[116:117], v[104:105] op_sel:[1,0]
	v_pk_mul_f32 v[104:105], v[116:117], v[94:95] op_sel:[1,0]
	s_waitcnt vmcnt(4)
	v_pk_fma_f32 v[90:91], v[90:91], v[128:129], v[132:133]
	v_pk_fma_f32 v[128:129], v[100:101], v[130:131], v[134:135]
	v_pk_mul_f32 v[100:101], v[116:117], v[92:93] op_sel:[1,0]
	s_waitcnt vmcnt(2)
	v_pk_fma_f32 v[136:137], v[104:105], v[136:137], v[140:141]
	v_pk_fma_f32 v[138:139], v[100:101], v[138:139], v[142:143]
	v_pk_mul_f32 v[104:105], v[116:117], v[96:97] op_sel:[1,0]
	s_waitcnt vmcnt(0)
; DI unsigned pkh2(float lo, float hi) { return __builtin_bit_cast(unsigned, __builtin_amdgcn_cvt_pkrtz(lo, hi)); }
; DI void lnmod_phase(const Args& A, LAS unsigned char* lds, int tid, int bid, int G, bool init, int l_norm, int i_norm, int l_mod, int i_mod, bool want_dt, int nrows, bool ctx_partial, const float* gprev, const float* bprev) {
;     ...
;             const float* t0 = (const float*)(A.ws + WS_T) + (size_t)(row - M_LAT) * DM; const float* t1 = t0 + (size_t)M_CTX * DM; const float* t2 = t1 + (size_t)M_CTX * DM; const float* t3 = t2 + (size_t)M_CTX * DM;
; #pragma unroll
;             for (int j = 0; j < 4; ++j) { v[j] = v[j] * ALPHA + (*(const f32x4*)(t0 + 256 * j + 4 * lane) + *(const f32x4*)(t1 + 256 * j + 4 * lane)) + (*(const f32x4*)(t2 + 256 * j + 4 * lane) + *(const f32x4*)(t3 + 256 * j + 4 * lane)); u32x2 w_; w_.x = pkh2(v[j].x, v[j].y); w_.y = pkh2(v[j].z, v[j].w); *(u32x2*)(xout + 256 * j + 4 * lane) = w_; }
	v_pk_fma_f32 v[154:155], v[106:107], v[154:155], v[160:161]
	v_lshlrev_b64 v[100:101], 12, v[146:147]
	v_lshl_add_u64 v[100:101], s[24:25], 0, v[100:101]
	v_lshlrev_b32_e32 v146, 2, v66
	v_lshl_add_u64 v[106:107], v[100:101], 0, v[146:147]
	v_add_co_u32_e32 v124, vcc, s9, v106
	global_load_dwordx4 v[112:115], v[106:107], off
	s_nop 1
	v_addc_co_u32_e32 v125, vcc, 0, v107, vcc
	global_load_dwordx4 v[116:119], v[124:125], off
	s_mov_b64 s[24:25], 0x800000
	v_lshl_add_u64 v[110:111], v[106:107], 0, s[24:25]
	s_mov_b64 s[24:25], 0x1000000
	v_lshl_add_u64 v[126:127], v[106:107], 0, s[24:25]
	s_mov_b64 s[24:25], 0x1800000
	v_lshl_add_u64 v[132:133], v[106:107], 0, s[24:25]
	s_mov_b32 s9, 0x1000000
	v_add_co_u32_e32 v134, vcc, s9, v106
	s_nop 1
	v_addc_co_u32_e32 v135, vcc, 0, v107, vcc
	s_mov_b32 s9, 0x1800000
	global_load_dwordx4 v[140:143], v[134:135], off
	v_add_co_u32_e32 v164, vcc, s9, v106
	s_nop 1
	v_addc_co_u32_e32 v165, vcc, 0, v107, vcc
	global_load_dwordx4 v[166:169], v[164:165], off
	global_load_dwordx4 v[170:173], v[106:107], off offset:1024
	global_load_dwordx4 v[174:177], v[110:111], off offset:1024
	global_load_dwordx4 v[178:181], v[126:127], off offset:1024
	global_load_dwordx4 v[182:185], v[132:133], off offset:1024
	global_load_dwordx4 v[186:189], v[106:107], off offset:2048
	global_load_dwordx4 v[190:193], v[110:111], off offset:2048
	global_load_dwordx4 v[194:197], v[126:127], off offset:2048
	global_load_dwordx4 v[198:201], v[132:133], off offset:2048
	global_load_dwordx4 v[202:205], v[106:107], off offset:3072
	global_load_dwordx4 v[218:221], v[110:111], off offset:3072
	global_load_dwordx4 v[222:225], v[126:127], off offset:3072
	global_load_dwordx4 v[226:229], v[132:133], off offset:3072
	s_nop 0
	v_pk_fma_f32 v[156:157], v[104:105], v[156:157], v[162:163]
	s_mov_b32 s24, 0x3fd744fd
	s_waitcnt vmcnt(14)
	v_pk_add_f32 v[124:125], v[114:115], v[118:119]
	s_nop 0
	v_pk_fma_f32 v[88:89], v[88:89], s[24:25], v[124:125] op_sel_hi:[1,0,1]
	v_pk_add_f32 v[112:113], v[112:113], v[116:117]
	s_nop 0
	v_pk_fma_f32 v[120:121], v[120:121], s[24:25], v[112:113] op_sel_hi:[1,0,1]
	s_mov_b32 s9, 0x21200000
	s_nop 0
	s_waitcnt vmcnt(12)
	v_pk_add_f32 v[164:165], v[142:143], v[168:169]
	v_pk_add_f32 v[140:141], v[140:141], v[166:167]
	v_pk_add_f32 v[164:165], v[88:89], v[164:165]
	v_pk_add_f32 v[88:89], v[120:121], v[140:141]
	v_add_co_u32_e32 v140, vcc, s9, v86
	v_cvt_pkrtz_f16_f32 v142, v88, v89
	v_cvt_pkrtz_f16_f32 v143, v164, v165
	v_addc_co_u32_e32 v141, vcc, 0, v87, vcc
	global_store_dwordx2 v[140:141], v[142:143], off
	s_nop 0
	s_waitcnt vmcnt(11)
	v_pk_add_f32 v[172:173], v[172:173], v[176:177]
	v_pk_add_f32 v[170:171], v[170:171], v[174:175]
	v_pk_fma_f32 v[128:129], v[128:129], s[24:25], v[172:173] op_sel_hi:[1,0,1]
	v_pk_fma_f32 v[90:91], v[90:91], s[24:25], v[170:171] op_sel_hi:[1,0,1]
	s_waitcnt vmcnt(9)
	v_pk_add_f32 v[180:181], v[180:181], v[184:185]
	v_pk_add_f32 v[178:179], v[178:179], v[182:183]
	v_pk_add_f32 v[122:123], v[128:129], v[180:181]
	v_pk_add_f32 v[90:91], v[90:91], v[178:179]
	v_cvt_pkrtz_f16_f32 v129, v122, v123
	v_cvt_pkrtz_f16_f32 v128, v90, v91
	global_store_dwordx2 v[140:141], v[128:129], off offset:512
	s_waitcnt vmcnt(8)
	v_pk_add_f32 v[128:129], v[188:189], v[192:193]
	v_pk_add_f32 v[186:187], v[186:187], v[190:191]
	v_pk_fma_f32 v[128:129], v[138:139], s[24:25], v[128:129] op_sel_hi:[1,0,1]
	v_pk_fma_f32 v[190:191], v[136:137], s[24:25], v[186:187] op_sel_hi:[1,0,1]
	s_waitcnt vmcnt(6)
	v_pk_add_f32 v[196:197], v[196:197], v[200:201]
	v_pk_add_f32 v[198:199], v[194:195], v[198:199]
	v_pk_add_f32 v[194:195], v[128:129], v[196:197]
	v_pk_add_f32 v[196:197], v[190:191], v[198:199]
	v_cvt_pkrtz_f16_f32 v129, v194, v195
	v_cvt_pkrtz_f16_f32 v128, v196, v197
	global_store_dwordx2 v[140:141], v[128:129], off offset:1024
	s_nop 0
	s_waitcnt vmcnt(5)
	v_pk_add_f32 v[204:205], v[204:205], v[220:221]
	v_pk_add_f32 v[202:203], v[202:203], v[218:219]
	v_pk_fma_f32 v[204:205], v[156:157], s[24:25], v[204:205] op_sel_hi:[1,0,1]
	v_pk_fma_f32 v[202:203], v[154:155], s[24:25], v[202:203] op_sel_hi:[1,0,1]
	s_nop 0
	s_waitcnt vmcnt(3)
	v_pk_add_f32 v[224:225], v[224:225], v[228:229]
	v_pk_add_f32 v[226:227], v[222:223], v[226:227]
	v_pk_add_f32 v[222:223], v[204:205], v[224:225]
	v_pk_add_f32 v[224:225], v[202:203], v[226:227]
	v_cvt_pkrtz_f16_f32 v227, v222, v223
	v_cvt_pkrtz_f16_f32 v226, v224, v225
	global_store_dwordx2 v[140:141], v[226:227], off offset:1536
	v_mov_b32_e32 v228, v89
	v_mov_b32_e32 v229, v164
	v_mov_b32_e32 v89, v165
	v_mov_b32_e32 v164, v91
	v_mov_b32_e32 v165, v122
	v_mov_b32_e32 v91, v123
	v_mov_b32_e32 v226, v225
	v_mov_b32_e32 v202, v223
	v_mov_b32_e32 v92, v194
	v_mov_b32_e32 v93, v195
	v_mov_b32_e32 v94, v196
	v_mov_b32_e32 v95, v197
	v_mov_b32_e32 v96, v222
	v_mov_b32_e32 v98, v224
	v_mov_b32_e32 v100, v164
	v_mov_b32_e32 v101, v165
	v_mov_b32_e32 v102, v226
	v_mov_b32_e32 v104, v228
	v_mov_b32_e32 v105, v229
	v_mov_b32_e32 v106, v202

; #define ATT_STORE(buf) do { _Pragma("unroll") for (int i_ = 0; i_ < 2; ++i_) { const int c_ = tid + 512 * i_; const int key_ = c_ >> 4, part_ = c_ & 15, e_ = c_ >> 3, vp_ = c_ & 7; \
;         *(LAS u32x4*)(lds + (buf) * KBYTES + (key_ * KP + part_ * 8) * 2) = kreg[i_]; \
;         *(LAS u32x4*)(lds + 3 * KBYTES + (buf) * VBYTES + (e_ * VP + vp_ * 8) * 2) = vreg[i_]; } } while (0)
; #define ATT_PV(bufv) do { \
;         const LAS bf16* Vb = (const LAS bf16*)(lds + 3 * KBYTES + (bufv) * VBYTES) + hi * 8; \
;         _Pragma("unroll") for (int es = 0; es < 4; ++es) _Pragma("unroll") for (int kk = 0; kk < 4; ++kk) { \
;             const bf16x8 a = *(const LAS bf16x8*)(Vb + (es * 32 + r32) * VP + kk * 16); O[es] = MFMA32(a, pf[kk], O[es]); } } while (0)
; DI void attn_unit(LAS unsigned char* lds, int tid, const bf16* __restrict__ P, const bf16* __restrict__ Vt, bf16* MG, int b, int h, int qrow0, int jt0, int jt1,
;                   float lam, float oscale, const float* subg) {
;     ...
;     __syncthreads();
;     ATT_LOADG(jt0);
;     int buf = 0, pbuf = 2;
;     for (int j = jt0; j < jt1; ++j) {
;         ATT_STORE(buf);
;         __syncthreads();
;         if (j + 1 < jt1) ATT_LOADG(j + 1);
;         if (!halfB) { ATT_QKS(buf, j == jt0); ATT_PV(buf); }
;         else { if (j > jt0) { ATT_PV(pbuf); } ATT_QKS(buf, j == jt0); }
.LBB0_300:
	s_mov_b32 s19, s2
	s_mulk_i32 s2, 0x4400
	s_add_i32 s3, s2, 0
	s_lshl_b32 s20, s19, 10
	s_add_i32 s20, s3, s20
	v_add_u32_e32 v246, s3, v171
	v_add_u32_e32 v247, s20, v172
	s_waitcnt vmcnt(2)
	ds_write_b128 v246, v[132:135]
	s_waitcnt vmcnt(1)
	ds_write_b128 v247, v[128:131] offset:52224
	ds_write_b128 v246, v[136:139] offset:8704
	s_waitcnt vmcnt(0)
	ds_write_b128 v247, v[140:143] offset:61440
	v_add_u32_e32 v173, s2, v175
	s_mul_i32 s22, s21, 0x4800
	s_add_i32 s22, s22, 0xcc00
	v_add_u32_e32 v250, s22, v178
	ds_read_b128 v[188:191], v250
	ds_read_b128 v[192:195], v250 offset:4608
	ds_read_b128 v[196:199], v250 offset:9216
	ds_read_b128 v[200:203], v250 offset:13824
	ds_read_b128 v[204:207], v250 offset:32
	ds_read_b128 v[218:221], v250 offset:4640
	ds_read_b128 v[222:225], v250 offset:9248
	ds_read_b128 v[226:229], v250 offset:13856
	ds_read_b128 v[230:233], v250 offset:64
	ds_read_b128 v[234:237], v250 offset:4672
	ds_read_b128 v[238:241], v250 offset:9280
	s_cmp_eq_u32 s17, 0
	s_cbranch_scc1 .Latt1_first
	s_waitcnt lgkmcnt(10)
	v_mfma_f32_32x32x16_bf16 v[48:63], v[188:191], v[80:83], v[48:63]
	s_cmpk_lg_i32 s17, 0x1080
	s_cbranch_scc0 .Latt1_noload_a
	s_cmp_lt_u32 s18, 63
	s_cselect_b32 s3, s16, s15
	s_add_i32 s3, s3, s17
	v_add_u32_e32 v188, s3, v155
	v_mad_i64_i32 v[188:189], s[22:23], v188, s72, v[160:161]
	v_add_u32_e32 v190, s3, v170
	global_load_dwordx4 v[128:131], v[162:163], off
	v_mad_i64_i32 v[190:191], s[22:23], v190, s72, v[160:161]
	global_load_dwordx4 v[132:135], v[188:189], off offset:1024
	global_load_dwordx4 v[136:139], v[190:191], off offset:1024
	global_load_dwordx4 v[140:143], v[164:165], off
.Latt1_noload_a:
	ds_read_b128 v[242:245], v250 offset:13888
	v_exp_f32_e32 v88, v88
	v_exp_f32_e32 v89, v89
	v_exp_f32_e32 v90, v90
	s_waitcnt lgkmcnt(10)
	v_mfma_f32_32x32x16_bf16 v[32:47], v[192:195], v[80:83], v[32:47]
	ds_read_b128 v[246:249], v250 offset:96
	v_exp_f32_e32 v91, v91
	v_exp_f32_e32 v92, v92
	v_exp_f32_e32 v93, v93
	v_add_f32_e32 v145, v145, v88
	v_add_f32_e32 v146, v146, v89
	s_waitcnt lgkmcnt(10)
	v_mfma_f32_32x32x16_bf16 v[16:31], v[196:199], v[80:83], v[16:31]
	ds_read_b128 v[180:183], v250 offset:4704
	v_exp_f32_e32 v94, v94
	v_exp_f32_e32 v95, v95
	v_add_f32_e32 v150, v150, v90
	v_add_f32_e32 v151, v151, v91
	v_add_f32_e32 v145, v145, v92
	v_add_f32_e32 v146, v146, v93
	s_waitcnt lgkmcnt(10)
	v_mfma_f32_32x32x16_bf16 v[0:15], v[200:203], v[80:83], v[0:15]
	ds_read_b128 v[184:187], v250 offset:9312
	v_cvt_pk_bf16_f32 v88, v88, v89
	v_cvt_pk_bf16_f32 v89, v90, v91
	v_cvt_pk_bf16_f32 v90, v92, v93
	v_cvt_pk_bf16_f32 v91, v94, v95
	v_add_f32_e32 v150, v150, v94
	v_add_f32_e32 v151, v151, v95
	s_waitcnt lgkmcnt(10)
	v_mfma_f32_32x32x16_bf16 v[48:63], v[204:207], v[88:91], v[48:63]
	ds_read_b128 v[188:191], v250 offset:13920
	v_exp_f32_e32 v96, v96
	v_exp_f32_e32 v97, v97
	v_exp_f32_e32 v98, v98
	s_waitcnt lgkmcnt(10)
	v_mfma_f32_32x32x16_bf16 v[32:47], v[218:221], v[88:91], v[32:47]
	v_exp_f32_e32 v99, v99
	v_exp_f32_e32 v100, v100
	v_exp_f32_e32 v101, v101
	v_add_f32_e32 v145, v145, v96
	v_add_f32_e32 v146, v146, v97
	s_waitcnt lgkmcnt(9)
	v_mfma_f32_32x32x16_bf16 v[16:31], v[222:225], v[88:91], v[16:31]
	v_exp_f32_e32 v102, v102
	v_exp_f32_e32 v103, v103
	v_add_f32_e32 v150, v150, v98
	v_add_f32_e32 v151, v151, v99
	v_add_f32_e32 v145, v145, v100
	v_add_f32_e32 v146, v146, v101
	s_waitcnt lgkmcnt(8)
	v_mfma_f32_32x32x16_bf16 v[0:15], v[226:229], v[88:91], v[0:15]
	v_cvt_pk_bf16_f32 v96, v96, v97
	v_cvt_pk_bf16_f32 v97, v98, v99
	v_cvt_pk_bf16_f32 v98, v100, v101
	v_cvt_pk_bf16_f32 v99, v102, v103
	v_add_f32_e32 v150, v150, v102
	v_add_f32_e32 v151, v151, v103
	s_barrier
	ds_read_b128 v[192:195], v173
	ds_read_b128 v[196:199], v173 offset:8704
	ds_read_b128 v[200:203], v173 offset:32
	ds_read_b128 v[204:207], v173 offset:8736
	ds_read_b128 v[218:221], v173 offset:64
	ds_read_b128 v[222:225], v173 offset:8768
	ds_read_b128 v[226:229], v173 offset:96
	s_waitcnt lgkmcnt(14)
	v_mfma_f32_32x32x16_bf16 v[48:63], v[230:233], v[96:99], v[48:63]
	ds_read_b128 v[230:233], v173 offset:8800
	v_exp_f32_e32 v104, v104
	v_exp_f32_e32 v105, v105
	v_exp_f32_e32 v106, v106
	s_waitcnt lgkmcnt(14)
	v_mfma_f32_32x32x16_bf16 v[32:47], v[234:237], v[96:99], v[32:47]
	v_exp_f32_e32 v107, v107
	v_exp_f32_e32 v108, v108
	v_exp_f32_e32 v109, v109
	v_add_f32_e32 v145, v145, v104
	v_add_f32_e32 v146, v146, v105
	s_waitcnt lgkmcnt(13)
	v_mfma_f32_32x32x16_bf16 v[16:31], v[238:241], v[96:99], v[16:31]
	v_exp_f32_e32 v110, v110
	v_exp_f32_e32 v111, v111
	v_add_f32_e32 v150, v150, v106
	v_add_f32_e32 v151, v151, v107
	v_add_f32_e32 v145, v145, v108
	v_add_f32_e32 v146, v146, v109
	s_waitcnt lgkmcnt(12)
	v_mfma_f32_32x32x16_bf16 v[0:15], v[242:245], v[96:99], v[0:15]
	v_cvt_pk_bf16_f32 v104, v104, v105
	v_cvt_pk_bf16_f32 v105, v106, v107
	v_cvt_pk_bf16_f32 v106, v108, v109
	v_cvt_pk_bf16_f32 v107, v110, v111
	v_add_f32_e32 v150, v150, v110
	v_add_f32_e32 v151, v151, v111
	s_waitcnt lgkmcnt(11)
	v_mfma_f32_32x32x16_bf16 v[48:63], v[246:249], v[104:107], v[48:63]
	v_add_f32_e32 v145, v145, v146
	s_waitcnt lgkmcnt(10)
	v_mfma_f32_32x32x16_bf16 v[32:47], v[180:183], v[104:107], v[32:47]
	v_add_f32_e32 v150, v150, v151
	s_waitcnt lgkmcnt(9)
	v_mfma_f32_32x32x16_bf16 v[16:31], v[184:187], v[104:107], v[16:31]
	v_add_f32_e32 v145, v145, v150
	s_waitcnt lgkmcnt(8)
	v_mfma_f32_32x32x16_bf16 v[0:15], v[188:191], v[104:107], v[0:15]
	v_add_f32_e32 v158, v158, v145
	s_branch .Latt1_qk
; #define ATT_STORE(buf) do { _Pragma("unroll") for (int i_ = 0; i_ < 2; ++i_) { const int c_ = tid + 512 * i_; const int key_ = c_ >> 4, part_ = c_ & 15, e_ = c_ >> 3, vp_ = c_ & 7; \
;         *(LAS u32x4*)(lds + (buf) * KBYTES + (key_ * KP + part_ * 8) * 2) = kreg[i_]; \
;         *(LAS u32x4*)(lds + 3 * KBYTES + (buf) * VBYTES + (e_ * VP + vp_ * 8) * 2) = vreg[i_]; } } while (0)
; #define ATT_PV(bufv) do { \
;         const LAS bf16* Vb = (const LAS bf16*)(lds + 3 * KBYTES + (bufv) * VBYTES) + hi * 8; \
;         _Pragma("unroll") for (int es = 0; es < 4; ++es) _Pragma("unroll") for (int kk = 0; kk < 4; ++kk) { \
;             const bf16x8 a = *(const LAS bf16x8*)(Vb + (es * 32 + r32) * VP + kk * 16); O[es] = MFMA32(a, pf[kk], O[es]); } } while (0)
; DI void attn_unit(LAS unsigned char* lds, int tid, const bf16* __restrict__ P, const bf16* __restrict__ Vt, bf16* MG, int b, int h, int qrow0, int jt0, int jt1,
;                   float lam, float oscale, const float* subg) {
;     ...
;     __syncthreads();
;     ATT_LOADG(jt0);
;     int buf = 0, pbuf = 2;
;     for (int j = jt0; j < jt1; ++j) {
;         ATT_STORE(buf);
;         __syncthreads();
;         if (j + 1 < jt1) ATT_LOADG(j + 1);
;         if (!halfB) { ATT_QKS(buf, j == jt0); ATT_PV(buf); }
;         else { if (j > jt0) { ATT_PV(pbuf); } ATT_QKS(buf, j == jt0); }
.Latt1_first:
	s_waitcnt lgkmcnt(10)
	v_mfma_f32_32x32x16_bf16 v[48:63], v[188:191], v[80:83], v[48:63]
	s_cmpk_lg_i32 s17, 0x1080
	s_cbranch_scc0 .Latt1_noload_b
	s_cmp_lt_u32 s18, 63
	s_cselect_b32 s3, s16, s15
	s_add_i32 s3, s3, s17
	v_add_u32_e32 v188, s3, v155
	v_mad_i64_i32 v[188:189], s[22:23], v188, s72, v[160:161]
	v_add_u32_e32 v190, s3, v170
	global_load_dwordx4 v[128:131], v[162:163], off
	v_mad_i64_i32 v[190:191], s[22:23], v190, s72, v[160:161]
	global_load_dwordx4 v[132:135], v[188:189], off offset:1024
	global_load_dwordx4 v[136:139], v[190:191], off offset:1024
	global_load_dwordx4 v[140:143], v[164:165], off
.Latt1_noload_b:
	ds_read_b128 v[242:245], v250 offset:13888
	s_waitcnt lgkmcnt(10)
	v_mfma_f32_32x32x16_bf16 v[32:47], v[192:195], v[80:83], v[32:47]
	ds_read_b128 v[246:249], v250 offset:96
	s_waitcnt lgkmcnt(10)
	v_mfma_f32_32x32x16_bf16 v[16:31], v[196:199], v[80:83], v[16:31]
	ds_read_b128 v[180:183], v250 offset:4704
	s_waitcnt lgkmcnt(10)
	v_mfma_f32_32x32x16_bf16 v[0:15], v[200:203], v[80:83], v[0:15]
	ds_read_b128 v[184:187], v250 offset:9312
	s_waitcnt lgkmcnt(10)
	v_mfma_f32_32x32x16_bf16 v[48:63], v[204:207], v[88:91], v[48:63]
	ds_read_b128 v[188:191], v250 offset:13920
	s_waitcnt lgkmcnt(10)
	v_mfma_f32_32x32x16_bf16 v[32:47], v[218:221], v[88:91], v[32:47]
	s_waitcnt lgkmcnt(9)
	v_mfma_f32_32x32x16_bf16 v[16:31], v[222:225], v[88:91], v[16:31]
	s_waitcnt lgkmcnt(8)
	v_mfma_f32_32x32x16_bf16 v[0:15], v[226:229], v[88:91], v[0:15]
	s_barrier
	ds_read_b128 v[192:195], v173
	ds_read_b128 v[196:199], v173 offset:8704
	ds_read_b128 v[200:203], v173 offset:32
	ds_read_b128 v[204:207], v173 offset:8736
	ds_read_b128 v[218:221], v173 offset:64
	ds_read_b128 v[222:225], v173 offset:8768
	ds_read_b128 v[226:229], v173 offset:96
	s_waitcnt lgkmcnt(14)
	v_mfma_f32_32x32x16_bf16 v[48:63], v[230:233], v[84:87], v[48:63]
	ds_read_b128 v[230:233], v173 offset:8800
	s_waitcnt lgkmcnt(14)
	v_mfma_f32_32x32x16_bf16 v[32:47], v[234:237], v[84:87], v[32:47]
	s_waitcnt lgkmcnt(13)
	v_mfma_f32_32x32x16_bf16 v[16:31], v[238:241], v[84:87], v[16:31]
	s_waitcnt lgkmcnt(12)
	v_mfma_f32_32x32x16_bf16 v[0:15], v[242:245], v[84:87], v[0:15]
	s_waitcnt lgkmcnt(11)
	v_mfma_f32_32x32x16_bf16 v[48:63], v[246:249], v[92:95], v[48:63]
	s_waitcnt lgkmcnt(10)
	v_mfma_f32_32x32x16_bf16 v[32:47], v[180:183], v[92:95], v[32:47]
	s_waitcnt lgkmcnt(9)
	v_mfma_f32_32x32x16_bf16 v[16:31], v[184:187], v[92:95], v[16:31]
	s_waitcnt lgkmcnt(8)
	v_mfma_f32_32x32x16_bf16 v[0:15], v[188:191], v[92:95], v[0:15]
